# LRU carry scan moved from the tail of phase 7 to the idle tail of phase 6 (blocks with one unit per up-projection GEMM)
# speedup vs baseline: 1.0035x; 1.0035x over previous
; __device__ __forceinline__ void lru_carry(ArgP a, int item, int lane) {
;     const int bd = item / 6, ch = 64 * (item % 6) + lane, dir = bd & 1;
;     const float2* S = (const float2*)(a->ws + OFF_LRUS) + (size_t)bd * NCHUNK * 384 + ch; float* Cr = (float*)(a->ws + OFF_LRUC) + (size_t)bd * NCHUNK * 384 + ch;
;     float X = 0.f;
;     for (int i0 = 0; i0 < NCHUNK; i0 += 8) {
;         float2 s[8]; int ck[8];
; #pragma unroll
;         for (int j = 0; j < 8; ++j) { const int i = i0 + j;
;             ck[j] = dir == 0 ? i : (i < 8 ? 7 - i : NCHUNK + 7 - i); s[j] = S[(size_t)ck[j] * 384]; }
; #pragma unroll
;         for (int j = 0; j < 8; ++j) { Cr[(size_t)ck[j] * 384] = X; X = s[j].x * X + s[j].y; }
;     }
; }
; __global__ void __launch_bounds__(NTHR) fwd_megakernel(Args a_unused) {
;     ...
;                 if ((pm & 4) && wave == 0) { for (int item = G - 1 - bid; item < 48; item += G) lru_carry(a, item, lane); } }
.LBB0_758:
.LBB0_764:
	s_mov_b64 s[44:45], 0
	s_branch .LBB0_954

; __device__ __forceinline__ void lru_carry(ArgP a, int item, int lane) {
;     const int bd = item / 6, ch = 64 * (item % 6) + lane, dir = bd & 1;
;     const float2* S = (const float2*)(a->ws + OFF_LRUS) + (size_t)bd * NCHUNK * 384 + ch; float* Cr = (float*)(a->ws + OFF_LRUC) + (size_t)bd * NCHUNK * 384 + ch;
;     float X = 0.f;
.Lcarry_p6:
	s_and_b64 vcc, exec, s[0:1]
	s_cbranch_vccz .LBB0_1022
	v_mbcnt_lo_u32_b32 v1, -1, 0
	v_mbcnt_hi_u32_b32 v1, -1, v1
	v_readlane_b32 s0, v254, 48
	s_cmp_eq_u32 s0, 0
	s_cbranch_scc0 .LBB0_1022
	s_not_b32 s0, s89
	s_add_i32 s2, s90, s0
	s_cmp_gt_i32 s2, 47
	s_cbranch_scc1 .LBB0_1022
	s_add_u32 s3, s10, 0x200000
	s_addc_u32 s12, s11, 0
	s_add_u32 s13, s10, 0x900000
	s_addc_u32 s14, s11, 0

; __device__ __forceinline__ void lru_carry(ArgP a, int item, int lane) {
;     ...
;     for (int i0 = 0; i0 < NCHUNK; i0 += 8) {
;         float2 s[8]; int ck[8];
; #pragma unroll
;         for (int j = 0; j < 8; ++j) { const int i = i0 + j;
;             ck[j] = dir == 0 ? i : (i < 8 ? 7 - i : NCHUNK + 7 - i); s[j] = S[(size_t)ck[j] * 384]; }
; #pragma unroll
;         for (int j = 0; j < 8; ++j) { Cr[(size_t)ck[j] * 384] = X; X = s[j].x * X + s[j].y; }
;     }
.LBB0_762:
	s_add_i32 s16, s20, 7
	s_and_b64 s[26:27], s[0:1], exec
	s_cselect_b32 s21, s15, s16
	s_mul_i32 s16, s21, 0x180
	v_lshl_add_u64 v[8:9], s[16:17], 3, v[2:3]
	s_add_i32 s16, s20, 6
	s_add_i32 s18, s15, 1
	s_and_b64 s[26:27], s[0:1], exec
	s_cselect_b32 s26, s18, s16
	s_mul_i32 s16, s26, 0x180
	v_lshl_add_u64 v[10:11], s[16:17], 3, v[2:3]
	s_add_i32 s16, s20, 5
	s_add_i32 s18, s15, 2
	s_and_b64 s[28:29], s[0:1], exec
	s_cselect_b32 s18, s18, s16
	s_mul_i32 s16, s18, 0x180
	v_lshl_add_u64 v[12:13], s[16:17], 3, v[2:3]
	s_add_i32 s16, s20, 4
	s_add_i32 s19, s15, 3
	s_and_b64 s[28:29], s[0:1], exec
	s_cselect_b32 s19, s19, s16
	s_mul_i32 s16, s19, 0x180
	v_lshl_add_u64 v[14:15], s[16:17], 3, v[2:3]
	s_add_i32 s16, s20, 3
	s_add_i32 s27, s15, 4
	s_and_b64 s[28:29], s[0:1], exec
	s_cselect_b32 s34, s27, s16
	s_mul_i32 s16, s34, 0x180
	v_lshl_add_u64 v[16:17], s[16:17], 3, v[2:3]
	s_add_i32 s16, s20, 2
	s_add_i32 s27, s15, 5
	s_and_b64 s[28:29], s[0:1], exec
	s_cselect_b32 s35, s27, s16
	s_mul_i32 s16, s35, 0x180
	v_lshl_add_u64 v[18:19], s[16:17], 3, v[2:3]
	s_add_i32 s16, s20, 1
	s_add_i32 s27, s15, 6
	s_and_b64 s[28:29], s[0:1], exec
	global_load_dwordx2 v[8:9], v[8:9], off
	s_cselect_b32 s38, s27, s16
	global_load_dwordx2 v[10:11], v[10:11], off
	s_mul_i32 s16, s38, 0x180
	global_load_dwordx2 v[12:13], v[12:13], off
	v_lshl_add_u64 v[20:21], s[16:17], 3, v[2:3]
	s_add_i32 s16, s15, 7
	global_load_dwordx2 v[14:15], v[14:15], off
	s_and_b64 s[28:29], s[0:1], exec
	global_load_dwordx2 v[16:17], v[16:17], off
	s_cselect_b32 s39, s16, s20
	global_load_dwordx2 v[18:19], v[18:19], off
	s_mul_i32 s16, s39, 0x180
	global_load_dwordx2 v[20:21], v[20:21], off
	v_lshl_add_u64 v[22:23], s[16:17], 3, v[2:3]
	global_load_dwordx2 v[22:23], v[22:23], off
	v_mad_u64_u32 v[24:25], s[28:29], s21, v216, v[4:5]
	global_store_dword v[24:25], v7, off
	s_add_i32 s20, s20, -8
	s_add_i32 s16, s15, 8
	s_cmpk_lt_u32 s15, 0x100
	s_mov_b32 s15, s16
	s_waitcnt vmcnt(0)
	v_fmac_f32_e32 v9, v7, v8
	v_mad_u64_u32 v[6:7], s[26:27], s26, v216, v[4:5]
	v_fmac_f32_e32 v11, v9, v10
	global_store_dword v[6:7], v9, off
	v_mad_u64_u32 v[6:7], s[26:27], s18, v216, v[4:5]
	v_fmac_f32_e32 v13, v11, v12
	global_store_dword v[6:7], v11, off
	v_mad_u64_u32 v[6:7], s[26:27], s19, v216, v[4:5]
	v_fmac_f32_e32 v15, v13, v14
	global_store_dword v[6:7], v13, off
	v_mad_u64_u32 v[6:7], s[26:27], s34, v216, v[4:5]
	v_fmac_f32_e32 v17, v15, v16
	global_store_dword v[6:7], v15, off
	v_mad_u64_u32 v[6:7], s[26:27], s35, v216, v[4:5]
	v_fmac_f32_e32 v19, v17, v18
	global_store_dword v[6:7], v17, off
	v_mad_u64_u32 v[6:7], s[26:27], s38, v216, v[4:5]
	v_fmac_f32_e32 v21, v19, v20
	global_store_dword v[6:7], v19, off
	v_mad_u64_u32 v[6:7], s[26:27], s39, v216, v[4:5]
	v_fmac_f32_e32 v23, v21, v22
	global_store_dword v[6:7], v21, off
	v_mov_b32_e32 v7, v23
	s_cbranch_scc1 .LBB0_762
	s_add_i32 s2, s2, s90
	s_cmp_gt_i32 s2, 47
	s_cbranch_scc0 .LBB0_761
.LBB0_1022:
	v_readlane_b32 s44, v254, 54
	s_branch .LBB0_1090
